# lever 1/2 extended again: mem-attention last tile group-1 PV reads issued together with counted waits (all three PV copies de-serialised)
# baseline (speedup 1.0000x reference)
; #define GAS __attribute__((address_space(1)))
; __device__ __forceinline__ float bf_lo(unsigned w) { return __uint_as_float(w << 16); }
; __device__ __forceinline__ float bf_hi(unsigned w) { return __uint_as_float(w & 0xffff0000u); }
; template <int DQK, int DV, int RH, bool NEGM> ...
;     ...
;         float l = (lacc[hh][0] + lacc[hh][1]) + (lacc[hh][2] + lacc[hh][3]); l += __shfl_xor(l, 32);
;         const float inv = 1.f / l;
;         const size_t ro = (size_t)(wid * 32 * RH + hh * 32 + r32) * zpitch;
; #pragma unroll
;         for (int dt = 0; dt < DV / 32; ++dt)
; #pragma unroll
;             for (int i = 0; i < 4; ++i) {
;                 const int c = dt * 32 + 8 * i + 4 * hi;
;                 const u32x2 zw = *(const GAS u32x2*)(ZI + ro + c);
;                 u32x2 w;
;                 w.x = pk2(o[hh][dt][4 * i + 0] * inv * bf_lo(zw.x), o[hh][dt][4 * i + 1] * inv * bf_hi(zw.x));
;                 w.y = pk2(o[hh][dt][4 * i + 2] * inv * bf_lo(zw.y), o[hh][dt][4 * i + 3] * inv * bf_hi(zw.y));
;                 *(GAS u32x2*)(ZO + ro + c) = w;
.LBB0_897:
	v_exp_f32_e32 v95, v80
	v_add_u32_e32 v80, s36, v179
	v_exp_f32_e32 v93, v101
	v_exp_f32_e32 v101, v81
	v_add_u32_e32 v81, 0x8800, v80
	ds_read2_b64 v[110:113], v81 offset1:2
	v_exp_f32_e32 v91, v100
	v_exp_f32_e32 v90, v96
	v_exp_f32_e32 v92, v97
	v_exp_f32_e32 v97, v98
	v_exp_f32_e32 v99, v99
	v_exp_f32_e32 v96, v102
	v_exp_f32_e32 v98, v103
	v_cvt_pk_bf16_f32 v76, v91, v93
	v_cvt_pk_bf16_f32 v77, v90, v92
	v_cvt_pk_bf16_f32 v78, v97, v99
	v_cvt_pk_bf16_f32 v79, v96, v98
	ds_read2_b64 v[114:117], v81 offset0:4 offset1:6
	v_exp_f32_e32 v94, v82
	s_waitcnt lgkmcnt(1)
	v_mfma_f32_32x32x16_bf16 v[48:63], v[110:113], v[76:79], v[48:63]
	v_exp_f32_e32 v100, v83
	v_exp_f32_e32 v107, v84
	v_exp_f32_e32 v109, v85
	v_exp_f32_e32 v83, v104
	v_exp_f32_e32 v85, v105
	v_exp_f32_e32 v82, v72
	v_exp_f32_e32 v84, v73
	v_exp_f32_e32 v105, v74
	v_exp_f32_e32 v103, v75
	v_exp_f32_e32 v104, v70
	v_exp_f32_e32 v102, v71
	v_cvt_pk_bf16_f32 v72, v83, v85
	v_cvt_pk_bf16_f32 v73, v82, v84
	v_cvt_pk_bf16_f32 v74, v105, v103
	v_cvt_pk_bf16_f32 v75, v104, v102
	ds_read2_b64 v[118:121], v81 offset0:8 offset1:10
	v_exp_f32_e32 v106, v86
	s_waitcnt lgkmcnt(1)
	v_mfma_f32_32x32x16_bf16 v[48:63], v[114:117], v[72:75], v[48:63]
	v_exp_f32_e32 v108, v87
	v_exp_f32_e32 v87, v88
	v_exp_f32_e32 v86, v68
	v_exp_f32_e32 v88, v69
	v_cvt_pk_bf16_f32 v68, v95, v101
	v_cvt_pk_bf16_f32 v69, v94, v100
	v_cvt_pk_bf16_f32 v70, v107, v109
	v_cvt_pk_bf16_f32 v71, v106, v108
	ds_read2_b64 v[114:117], v81 offset0:12 offset1:14
	v_exp_f32_e32 v89, v89
	s_waitcnt lgkmcnt(1)
	v_mfma_f32_32x32x16_bf16 v[48:63], v[118:121], v[68:71], v[48:63]
	v_exp_f32_e32 v111, v64
	v_exp_f32_e32 v113, v65
	v_exp_f32_e32 v110, v66
	v_exp_f32_e32 v112, v67
	v_cvt_pk_bf16_f32 v64, v87, v89
	v_cvt_pk_bf16_f32 v65, v86, v88
	v_cvt_pk_bf16_f32 v66, v111, v113
	v_cvt_pk_bf16_f32 v67, v110, v112
	v_add_u32_e32 v81, 0x9800, v80
	v_pk_add_f32 v[90:91], v[90:91], v[94:95]
	s_waitcnt lgkmcnt(0)
	v_mfma_f32_32x32x16_bf16 v[48:63], v[114:117], v[64:67], v[48:63]
	ds_read2_b64 v[216:219], v81 offset0:32 offset1:34
	ds_read2_b64 v[220:223], v81 offset0:36 offset1:38
	ds_read2_b64 v[224:227], v81 offset0:40 offset1:42
	ds_read2_b64 v[228:231], v81 offset0:44 offset1:46
	v_add_f32_e64 v92, v92, v100
	v_add_f32_e64 v93, v93, v101
	v_add_f32_e64 v94, v96, v106
	v_add_f32_e64 v95, v97, v107
	v_pk_add_f32 v[96:97], v[98:99], v[108:109]
	v_pk_add_f32 v[90:91], v[150:151], v[90:91]
	v_pk_add_f32 v[92:93], v[148:149], v[92:93]
	v_pk_add_f32 v[82:83], v[82:83], v[86:87]
	s_waitcnt lgkmcnt(3)
	v_mfma_f32_32x32x16_bf16 v[32:47], v[216:219], v[76:79], v[32:47]
	v_add_f32_e64 v84, v84, v88
	v_add_f32_e64 v85, v85, v89
	v_add_f32_e64 v90, v94, v90
	v_add_f32_e64 v91, v95, v91
	v_pk_add_f32 v[86:87], v[104:105], v[110:111]
	v_pk_add_f32 v[88:89], v[102:103], v[112:113]
	s_add_i32 s87, s87, s18
	s_add_i32 s88, s88, s20
	s_waitcnt lgkmcnt(2)
	v_mfma_f32_32x32x16_bf16 v[32:47], v[220:223], v[72:75], v[32:47]
	s_cmpk_gt_i32 s87, 0x1ff
	s_waitcnt lgkmcnt(1)
	v_mfma_f32_32x32x16_bf16 v[32:47], v[224:227], v[68:71], v[32:47]
	v_add_u32_e32 v81, 0xa800, v80
	v_add_u32_e32 v80, 0xb800, v80
	s_waitcnt lgkmcnt(0)
	v_mfma_f32_32x32x16_bf16 v[32:47], v[228:231], v[64:67], v[32:47]
	ds_read2_b64 v[114:117], v81 offset0:64 offset1:66
	ds_read2_b64 v[118:121], v81 offset0:68 offset1:70
	s_waitcnt lgkmcnt(1)
	v_mfma_f32_32x32x16_bf16 v[16:31], v[114:117], v[76:79], v[16:31]
	ds_read2_b64 v[114:117], v81 offset0:72 offset1:74
	ds_read2_b64 v[122:125], v81 offset0:76 offset1:78
	ds_read2_b64 v[126:129], v80 offset0:96 offset1:98
	ds_read2_b64 v[130:133], v80 offset0:100 offset1:102
	ds_read2_b64 v[134:137], v80 offset0:104 offset1:106
	ds_read2_b64 v[138:141], v80 offset0:108 offset1:110
	v_lshlrev_b32_e32 v80, 3, v178
	v_ashrrev_i32_e32 v81, 31, v80
	v_lshl_add_u64 v[80:81], v[80:81], 1, v[146:147]
	s_waitcnt lgkmcnt(0)
	s_barrier
	global_load_dwordx4 v[98:101], v[80:81], off offset:2048
	global_load_dwordx4 v[102:105], v[80:81], off offset:2080
	v_mfma_f32_32x32x16_bf16 v[16:31], v[118:121], v[72:75], v[16:31]
	global_load_dwordx4 v[106:109], v[80:81], off offset:2112
	v_mfma_f32_32x32x16_bf16 v[0:15], v[126:129], v[76:79], v[0:15]
	v_add_f32_e64 v76, v96, v92
	v_add_f32_e64 v77, v97, v93
	v_add_f32_e64 v78, v82, v90
	v_add_f32_e64 v79, v83, v91
	v_add_f32_e64 v76, v84, v76
	v_add_f32_e64 v77, v85, v77
	v_pk_add_f32 v[78:79], v[86:87], v[78:79]
	v_pk_add_f32 v[76:77], v[88:89], v[76:77]
	global_load_dwordx4 v[110:113], v[80:81], off offset:2144
	v_pk_add_f32 v[76:77], v[76:77], v[78:79]
	v_mfma_f32_32x32x16_bf16 v[16:31], v[114:117], v[68:71], v[16:31]
	global_load_dwordx4 v[118:121], v[80:81], off offset:2176
	v_add_f32_e32 v76, v76, v77
	ds_bpermute_b32 v77, v153, v76
	v_mfma_f32_32x32x16_bf16 v[0:15], v[130:133], v[72:75], v[0:15]
	s_waitcnt lgkmcnt(0)
	v_add_f32_e32 v74, v76, v77
	v_div_scale_f32 v75, s[6:7], v74, v74, 1.0
	v_rcp_f32_e32 v76, v75
	global_load_dwordx4 v[126:129], v[80:81], off offset:2208
	v_mfma_f32_32x32x16_bf16 v[0:15], v[134:137], v[68:71], v[0:15]
	v_fma_f32 v68, -v75, v76, 1.0
	v_fmac_f32_e32 v76, v68, v76
	v_div_scale_f32 v70, vcc, 1.0, v74, 1.0
	v_mul_f32_e32 v71, v70, v76
	v_fma_f32 v77, -v75, v71, v70
	global_load_dwordx4 v[114:117], v[80:81], off offset:2240
	v_fmac_f32_e32 v71, v77, v76
	v_mfma_f32_32x32x16_bf16 v[16:31], v[122:125], v[64:67], v[16:31]
	v_mfma_f32_32x32x16_bf16 v[0:15], v[138:141], v[64:67], v[0:15]
	global_load_dwordx4 v[130:133], v[80:81], off offset:2272
	v_fma_f32 v64, -v75, v71, v70
	v_div_fmas_f32 v64, v64, v76, v71
	v_div_fixup_f32 v64, v64, v74, 1.0
	s_waitcnt vmcnt(7)
; #define GAS __attribute__((address_space(1)))
; __device__ __forceinline__ float bf_lo(unsigned w) { return __uint_as_float(w << 16); }
; __device__ __forceinline__ float bf_hi(unsigned w) { return __uint_as_float(w & 0xffff0000u); }
; template <int DQK, int DV, int RH, bool NEGM> ...
;     ...
;         float l = (lacc[hh][0] + lacc[hh][1]) + (lacc[hh][2] + lacc[hh][3]); l += __shfl_xor(l, 32);
;         const float inv = 1.f / l;
;         const size_t ro = (size_t)(wid * 32 * RH + hh * 32 + r32) * zpitch;
; #pragma unroll
;         for (int dt = 0; dt < DV / 32; ++dt)
; #pragma unroll
;             for (int i = 0; i < 4; ++i) {
;                 const int c = dt * 32 + 8 * i + 4 * hi;
;                 const u32x2 zw = *(const GAS u32x2*)(ZI + ro + c);
;                 u32x2 w;
;                 w.x = pk2(o[hh][dt][4 * i + 0] * inv * bf_lo(zw.x), o[hh][dt][4 * i + 1] * inv * bf_hi(zw.x));
;                 w.y = pk2(o[hh][dt][4 * i + 2] * inv * bf_lo(zw.y), o[hh][dt][4 * i + 3] * inv * bf_hi(zw.y));
;                 *(GAS u32x2*)(ZO + ro + c) = w;
;             }
	v_permlane32_swap_b32_e32 v98, v100
	v_permlane32_swap_b32_e32 v99, v101
	v_pk_mul_f32 v[48:49], v[48:49], v[64:65] op_sel_hi:[1,0]
	v_pk_mul_f32 v[50:51], v[50:51], v[64:65] op_sel_hi:[1,0]
	v_lshlrev_b32_e32 v66, 16, v98
	v_and_b32_e32 v67, 0xffff0000, v98
	v_lshlrev_b32_e32 v70, 16, v99
	v_and_b32_e32 v71, 0xffff0000, v99
	v_pk_mul_f32 v[48:49], v[48:49], v[66:67]
	v_pk_mul_f32 v[50:51], v[50:51], v[70:71]
	v_pk_mul_f32 v[52:53], v[52:53], v[64:65] op_sel_hi:[1,0]
	v_pk_mul_f32 v[54:55], v[54:55], v[64:65] op_sel_hi:[1,0]
	v_lshlrev_b32_e32 v68, 16, v100
	v_and_b32_e32 v69, 0xffff0000, v100
	v_lshlrev_b32_e32 v72, 16, v101
	v_and_b32_e32 v73, 0xffff0000, v101
	v_pk_mul_f32 v[52:53], v[52:53], v[68:69]
	v_pk_mul_f32 v[54:55], v[54:55], v[72:73]
	v_cvt_pk_bf16_f32 v48, v48, v49
	v_cvt_pk_bf16_f32 v49, v50, v51
	v_cvt_pk_bf16_f32 v50, v52, v53
	v_cvt_pk_bf16_f32 v51, v54, v55
	s_nop 1
	v_permlane32_swap_b32_e32 v48, v50
	v_permlane32_swap_b32_e32 v49, v51
	global_store_dwordx4 v[80:81], v[48:51], off offset:2048
	s_waitcnt vmcnt(7)
	v_permlane32_swap_b32_e32 v102, v104
	v_permlane32_swap_b32_e32 v103, v105
	v_pk_mul_f32 v[56:57], v[56:57], v[64:65] op_sel_hi:[1,0]
	v_pk_mul_f32 v[58:59], v[58:59], v[64:65] op_sel_hi:[1,0]
	v_lshlrev_b32_e32 v66, 16, v102
	v_and_b32_e32 v67, 0xffff0000, v102
	v_lshlrev_b32_e32 v70, 16, v103
	v_and_b32_e32 v71, 0xffff0000, v103
	v_pk_mul_f32 v[56:57], v[56:57], v[66:67]
	v_pk_mul_f32 v[58:59], v[58:59], v[70:71]
	v_pk_mul_f32 v[60:61], v[60:61], v[64:65] op_sel_hi:[1,0]
	v_pk_mul_f32 v[62:63], v[62:63], v[64:65] op_sel_hi:[1,0]
	v_lshlrev_b32_e32 v68, 16, v104
	v_and_b32_e32 v69, 0xffff0000, v104
	v_lshlrev_b32_e32 v72, 16, v105
	v_and_b32_e32 v73, 0xffff0000, v105
	v_pk_mul_f32 v[60:61], v[60:61], v[68:69]
	v_pk_mul_f32 v[62:63], v[62:63], v[72:73]
	v_cvt_pk_bf16_f32 v56, v56, v57
	v_cvt_pk_bf16_f32 v57, v58, v59
	v_cvt_pk_bf16_f32 v58, v60, v61
	v_cvt_pk_bf16_f32 v59, v62, v63
	s_nop 1
	v_permlane32_swap_b32_e32 v56, v58
	v_permlane32_swap_b32_e32 v57, v59
	global_store_dwordx4 v[80:81], v[56:59], off offset:2080
	s_waitcnt vmcnt(7)
	v_permlane32_swap_b32_e32 v106, v108
	v_permlane32_swap_b32_e32 v107, v109
	v_pk_mul_f32 v[32:33], v[32:33], v[64:65] op_sel_hi:[1,0]
	v_pk_mul_f32 v[34:35], v[34:35], v[64:65] op_sel_hi:[1,0]
	v_lshlrev_b32_e32 v66, 16, v106
	v_and_b32_e32 v67, 0xffff0000, v106
	v_lshlrev_b32_e32 v70, 16, v107
	v_and_b32_e32 v71, 0xffff0000, v107
	v_pk_mul_f32 v[32:33], v[32:33], v[66:67]
	v_pk_mul_f32 v[34:35], v[34:35], v[70:71]
	v_pk_mul_f32 v[36:37], v[36:37], v[64:65] op_sel_hi:[1,0]
	v_pk_mul_f32 v[38:39], v[38:39], v[64:65] op_sel_hi:[1,0]
	v_lshlrev_b32_e32 v68, 16, v108
	v_and_b32_e32 v69, 0xffff0000, v108
	v_lshlrev_b32_e32 v72, 16, v109
	v_and_b32_e32 v73, 0xffff0000, v109
	v_pk_mul_f32 v[36:37], v[36:37], v[68:69]
	v_pk_mul_f32 v[38:39], v[38:39], v[72:73]
	v_cvt_pk_bf16_f32 v32, v32, v33
	v_cvt_pk_bf16_f32 v33, v34, v35
	v_cvt_pk_bf16_f32 v34, v36, v37
	v_cvt_pk_bf16_f32 v35, v38, v39
	s_nop 1
	v_permlane32_swap_b32_e32 v32, v34
	v_permlane32_swap_b32_e32 v33, v35
	global_store_dwordx4 v[80:81], v[32:35], off offset:2112
	s_waitcnt vmcnt(7)
	v_permlane32_swap_b32_e32 v110, v112
	v_permlane32_swap_b32_e32 v111, v113
	v_pk_mul_f32 v[40:41], v[40:41], v[64:65] op_sel_hi:[1,0]
	v_pk_mul_f32 v[42:43], v[42:43], v[64:65] op_sel_hi:[1,0]
	v_lshlrev_b32_e32 v66, 16, v110
	v_and_b32_e32 v67, 0xffff0000, v110
	v_lshlrev_b32_e32 v70, 16, v111
	v_and_b32_e32 v71, 0xffff0000, v111
	v_pk_mul_f32 v[40:41], v[40:41], v[66:67]
	v_pk_mul_f32 v[42:43], v[42:43], v[70:71]
	v_pk_mul_f32 v[44:45], v[44:45], v[64:65] op_sel_hi:[1,0]
	v_pk_mul_f32 v[46:47], v[46:47], v[64:65] op_sel_hi:[1,0]
	v_lshlrev_b32_e32 v68, 16, v112
	v_and_b32_e32 v69, 0xffff0000, v112
	v_lshlrev_b32_e32 v72, 16, v113
	v_and_b32_e32 v73, 0xffff0000, v113
	v_pk_mul_f32 v[44:45], v[44:45], v[68:69]
	v_pk_mul_f32 v[46:47], v[46:47], v[72:73]
	v_cvt_pk_bf16_f32 v40, v40, v41
	v_cvt_pk_bf16_f32 v41, v42, v43
	v_cvt_pk_bf16_f32 v42, v44, v45
	v_cvt_pk_bf16_f32 v43, v46, v47
	s_nop 1
	v_permlane32_swap_b32_e32 v40, v42
	v_permlane32_swap_b32_e32 v41, v43
	global_store_dwordx4 v[80:81], v[40:43], off offset:2144
	s_waitcnt vmcnt(7)
; #define GAS __attribute__((address_space(1)))
; __device__ __forceinline__ float bf_lo(unsigned w) { return __uint_as_float(w << 16); }
; __device__ __forceinline__ float bf_hi(unsigned w) { return __uint_as_float(w & 0xffff0000u); }
; template <int DQK, int DV, int RH, bool NEGM> ...
;     ...
;         float l = (lacc[hh][0] + lacc[hh][1]) + (lacc[hh][2] + lacc[hh][3]); l += __shfl_xor(l, 32);
;         const float inv = 1.f / l;
;         const size_t ro = (size_t)(wid * 32 * RH + hh * 32 + r32) * zpitch;
; #pragma unroll
;         for (int dt = 0; dt < DV / 32; ++dt)
; #pragma unroll
;             for (int i = 0; i < 4; ++i) {
;                 const int c = dt * 32 + 8 * i + 4 * hi;
;                 const u32x2 zw = *(const GAS u32x2*)(ZI + ro + c);
;                 u32x2 w;
;                 w.x = pk2(o[hh][dt][4 * i + 0] * inv * bf_lo(zw.x), o[hh][dt][4 * i + 1] * inv * bf_hi(zw.x));
;                 w.y = pk2(o[hh][dt][4 * i + 2] * inv * bf_lo(zw.y), o[hh][dt][4 * i + 3] * inv * bf_hi(zw.y));
;                 *(GAS u32x2*)(ZO + ro + c) = w;
;             }
;     }
;     __syncthreads();
	v_permlane32_swap_b32_e32 v118, v120
	v_permlane32_swap_b32_e32 v119, v121
	v_pk_mul_f32 v[16:17], v[16:17], v[64:65] op_sel_hi:[1,0]
	v_pk_mul_f32 v[18:19], v[18:19], v[64:65] op_sel_hi:[1,0]
	v_lshlrev_b32_e32 v66, 16, v118
	v_and_b32_e32 v67, 0xffff0000, v118
	v_lshlrev_b32_e32 v70, 16, v119
	v_and_b32_e32 v71, 0xffff0000, v119
	v_pk_mul_f32 v[16:17], v[16:17], v[66:67]
	v_pk_mul_f32 v[18:19], v[18:19], v[70:71]
	v_pk_mul_f32 v[20:21], v[20:21], v[64:65] op_sel_hi:[1,0]
	v_pk_mul_f32 v[22:23], v[22:23], v[64:65] op_sel_hi:[1,0]
	v_lshlrev_b32_e32 v68, 16, v120
	v_and_b32_e32 v69, 0xffff0000, v120
	v_lshlrev_b32_e32 v72, 16, v121
	v_and_b32_e32 v73, 0xffff0000, v121
	v_pk_mul_f32 v[20:21], v[20:21], v[68:69]
	v_pk_mul_f32 v[22:23], v[22:23], v[72:73]
	v_cvt_pk_bf16_f32 v16, v16, v17
	v_cvt_pk_bf16_f32 v17, v18, v19
	v_cvt_pk_bf16_f32 v18, v20, v21
	v_cvt_pk_bf16_f32 v19, v22, v23
	s_nop 1
	v_permlane32_swap_b32_e32 v16, v18
	v_permlane32_swap_b32_e32 v17, v19
	global_store_dwordx4 v[80:81], v[16:19], off offset:2176
	s_waitcnt vmcnt(7)
	v_permlane32_swap_b32_e32 v126, v128
	v_permlane32_swap_b32_e32 v127, v129
	v_pk_mul_f32 v[24:25], v[24:25], v[64:65] op_sel_hi:[1,0]
	v_pk_mul_f32 v[26:27], v[26:27], v[64:65] op_sel_hi:[1,0]
	v_lshlrev_b32_e32 v66, 16, v126
	v_and_b32_e32 v67, 0xffff0000, v126
	v_lshlrev_b32_e32 v70, 16, v127
	v_and_b32_e32 v71, 0xffff0000, v127
	v_pk_mul_f32 v[24:25], v[24:25], v[66:67]
	v_pk_mul_f32 v[26:27], v[26:27], v[70:71]
	v_pk_mul_f32 v[28:29], v[28:29], v[64:65] op_sel_hi:[1,0]
	v_pk_mul_f32 v[30:31], v[30:31], v[64:65] op_sel_hi:[1,0]
	v_lshlrev_b32_e32 v68, 16, v128
	v_and_b32_e32 v69, 0xffff0000, v128
	v_lshlrev_b32_e32 v72, 16, v129
	v_and_b32_e32 v73, 0xffff0000, v129
	v_pk_mul_f32 v[28:29], v[28:29], v[68:69]
	v_pk_mul_f32 v[30:31], v[30:31], v[72:73]
	v_cvt_pk_bf16_f32 v24, v24, v25
	v_cvt_pk_bf16_f32 v25, v26, v27
	v_cvt_pk_bf16_f32 v26, v28, v29
	v_cvt_pk_bf16_f32 v27, v30, v31
	s_nop 1
	v_permlane32_swap_b32_e32 v24, v26
	v_permlane32_swap_b32_e32 v25, v27
	global_store_dwordx4 v[80:81], v[24:27], off offset:2208
	s_waitcnt vmcnt(7)
	v_permlane32_swap_b32_e32 v114, v116
	v_permlane32_swap_b32_e32 v115, v117
	v_pk_mul_f32 v[0:1], v[0:1], v[64:65] op_sel_hi:[1,0]
	v_pk_mul_f32 v[2:3], v[2:3], v[64:65] op_sel_hi:[1,0]
	v_lshlrev_b32_e32 v66, 16, v114
	v_and_b32_e32 v67, 0xffff0000, v114
	v_lshlrev_b32_e32 v70, 16, v115
	v_and_b32_e32 v71, 0xffff0000, v115
	v_pk_mul_f32 v[0:1], v[0:1], v[66:67]
	v_pk_mul_f32 v[2:3], v[2:3], v[70:71]
	v_pk_mul_f32 v[4:5], v[4:5], v[64:65] op_sel_hi:[1,0]
	v_pk_mul_f32 v[6:7], v[6:7], v[64:65] op_sel_hi:[1,0]
	v_lshlrev_b32_e32 v68, 16, v116
	v_and_b32_e32 v69, 0xffff0000, v116
	v_lshlrev_b32_e32 v72, 16, v117
	v_and_b32_e32 v73, 0xffff0000, v117
	v_pk_mul_f32 v[4:5], v[4:5], v[68:69]
	v_pk_mul_f32 v[6:7], v[6:7], v[72:73]
	v_cvt_pk_bf16_f32 v0, v0, v1
	v_cvt_pk_bf16_f32 v1, v2, v3
	v_cvt_pk_bf16_f32 v2, v4, v5
	v_cvt_pk_bf16_f32 v3, v6, v7
	s_nop 1
	v_permlane32_swap_b32_e32 v0, v2
	v_permlane32_swap_b32_e32 v1, v3
	global_store_dwordx4 v[80:81], v[0:3], off offset:2240
	s_waitcnt vmcnt(7)
	v_permlane32_swap_b32_e32 v130, v132
	v_permlane32_swap_b32_e32 v131, v133
	v_pk_mul_f32 v[8:9], v[8:9], v[64:65] op_sel_hi:[1,0]
	v_pk_mul_f32 v[10:11], v[10:11], v[64:65] op_sel_hi:[1,0]
	v_lshlrev_b32_e32 v66, 16, v130
	v_and_b32_e32 v67, 0xffff0000, v130
	v_lshlrev_b32_e32 v70, 16, v131
	v_and_b32_e32 v71, 0xffff0000, v131
	v_pk_mul_f32 v[8:9], v[8:9], v[66:67]
	v_pk_mul_f32 v[10:11], v[10:11], v[70:71]
	v_pk_mul_f32 v[12:13], v[12:13], v[64:65] op_sel_hi:[1,0]
	v_pk_mul_f32 v[14:15], v[14:15], v[64:65] op_sel_hi:[1,0]
	v_lshlrev_b32_e32 v68, 16, v132
	v_and_b32_e32 v69, 0xffff0000, v132
	v_lshlrev_b32_e32 v72, 16, v133
	v_and_b32_e32 v73, 0xffff0000, v133
	v_pk_mul_f32 v[12:13], v[12:13], v[68:69]
	v_pk_mul_f32 v[14:15], v[14:15], v[72:73]
	v_cvt_pk_bf16_f32 v8, v8, v9
	v_cvt_pk_bf16_f32 v9, v10, v11
	v_cvt_pk_bf16_f32 v10, v12, v13
	v_cvt_pk_bf16_f32 v11, v14, v15
	s_nop 1
	v_permlane32_swap_b32_e32 v8, v10
	v_permlane32_swap_b32_e32 v9, v11
	global_store_dwordx4 v[80:81], v[8:11], off offset:2272
	s_barrier
	s_cbranch_scc1 .LBB0_930
